# prep transposes deal re-tuned from measured class end times (A 1090, B 1885, C 2785 items)
# speedup vs baseline: 1.0019x; 1.0019x over previous
.LBB0_87:
	s_and_b64 s[0:1], s[0:1], s[8:9]
	s_movk_i32 s2, 0x700
	s_and_b64 s[0:1], s[0:1], exec
	s_cselect_b32 s8, s2, 0x1680
	v_readlane_b32 s0, v251, 46
	s_cmpk_lt_i32 s63, 0x80
	s_cbranch_scc1 .Ldeal_ab
	s_lshl_b32 s0, s0, 7
	s_add_i32 s0, s0, s63
	s_add_i32 s6, s0, 0xffffff80
	s_movk_i32 s7, 0x400
	s_movk_i32 s8, 0xae1
	s_branch .Ldeal_done
.Ldeal_ab:
	s_lshl_b32 s0, s0, 6
	s_add_i32 s0, s0, s63
	s_movk_i32 s7, 0x200
	s_cmpk_lt_i32 s63, 0x40
	s_cbranch_scc1 .Ldeal_a
	s_add_i32 s6, s0, 0xaa1
	s_movk_i32 s8, 0x123e
	s_branch .Ldeal_done
.Ldeal_a:
	s_add_i32 s6, s0, 0x123e
	s_movk_i32 s8, 0x1680
